# G4 split-K sample-row GEMM staged through LDS-DMA (16 rows x 64 B pieces, 4-slot ring per wave) instead of 16-row register loads
# speedup vs baseline: 1.0030x; 1.0030x over previous
.LBB0_1088:
	s_and_b32 s10, s14, 0xffffffe0
	s_and_b32 s2, s13, 0x70
	v_or_b32_e32 v8, s10, v12
	s_movk_i32 s11, 0x1600
	v_or_b32_e32 v5, s2, v12
	v_mad_i64_i32 v[10:11], s[2:3], v8, s11, v[2:3]
	v_mul_u32_u24_e32 v6, 0xb00, v5
	v_or_b32_e32 v8, 16, v8
	v_lshlrev_b32_e32 v194, 1, v6
	v_mad_i64_i32 v[8:9], s[2:3], v8, s11, v[2:3]
	v_lshl_add_u64 v[6:7], v[0:1], 0, v[194:195]
	s_andn2_b64 vcc, exec, s[8:9]
	v_add_u32_e32 v30, s12, v13
	v_mbcnt_lo_u32_b32 v40, -1, 0
	v_mbcnt_hi_u32_b32 v40, -1, v40
	v_lshrrev_b32_e32 v41, 2, v40
	v_lshrrev_b32_e32 v42, 4, v40
	v_and_b32_e32 v43, 3, v40
	v_xor_b32_e32 v43, v43, v42
	v_sub_u32_e32 v43, v43, v42
	v_lshlrev_b32_e32 v43, 4, v43
	s_and_b32 s16, s13, 0x70
	v_add_u32_e32 v44, s16, v41
	v_mad_u32_u24 v44, v44, s11, v43
	v_ashrrev_i32_e32 v45, 31, v44
	v_lshl_add_u64 v[44:45], v[0:1], 0, v[44:45]
	v_add_u32_e32 v46, s10, v41
	v_mad_u32_u24 v46, v46, s11, v43
	v_ashrrev_i32_e32 v47, 31, v46
	v_lshl_add_u64 v[46:47], v[2:3], 0, v[46:47]
	s_lshl_b32 s18, s11, 4
	s_mov_b32 s19, 0
	v_lshl_add_u64 v[48:49], v[46:47], 0, s[18:19]
	v_lshrrev_b32_e32 v50, 2, v12
	v_xor_b32_e32 v50, v50, v42
	v_lshlrev_b32_e32 v50, 4, v50
	v_lshl_or_b32 v50, v12, 6, v50
	s_mul_i32 s17, s89, 0x3000
	s_add_i32 s17, s17, 0x4000
	v_add_u32_e32 v50, s17, v50
	s_add_i32 m0, s17, 0
	s_nop 0
	global_load_lds_dwordx4 v[44:45], off
	s_add_i32 m0, s17, 1024
	s_nop 0
	global_load_lds_dwordx4 v[46:47], off
	s_add_i32 m0, s17, 2048
	s_nop 0
	global_load_lds_dwordx4 v[48:49], off
	s_add_i32 m0, s17, 3008
	s_nop 0
	global_load_lds_dwordx4 v[44:45], off offset:64
	s_add_i32 m0, s17, 4032
	s_nop 0
	global_load_lds_dwordx4 v[46:47], off offset:64
	s_add_i32 m0, s17, 5056
	s_nop 0
	global_load_lds_dwordx4 v[48:49], off offset:64
	s_add_i32 m0, s17, 6016
	s_nop 0
	global_load_lds_dwordx4 v[44:45], off offset:128
	s_add_i32 m0, s17, 7040
	s_nop 0
	global_load_lds_dwordx4 v[46:47], off offset:128
	s_add_i32 m0, s17, 8064
	s_nop 0
	global_load_lds_dwordx4 v[48:49], off offset:128
	s_add_i32 m0, s17, 9024
	s_nop 0
	global_load_lds_dwordx4 v[44:45], off offset:192
	s_add_i32 m0, s17, 10048
	s_nop 0
	global_load_lds_dwordx4 v[46:47], off offset:192
	s_add_i32 m0, s17, 11072
	s_nop 0
	global_load_lds_dwordx4 v[48:49], off offset:192
	s_waitcnt vmcnt(9)
	ds_read_b128 v[52:55], v50 offset:0
	ds_read_b128 v[56:59], v50 offset:1024
	ds_read_b128 v[60:63], v50 offset:2048
	s_waitcnt lgkmcnt(0)
	s_sub_i32 m0, s17, 256
	s_nop 0
	global_load_lds_dwordx4 v[44:45], off offset:256
	s_add_i32 m0, s17, 768
	s_nop 0
	global_load_lds_dwordx4 v[46:47], off offset:256
	s_add_i32 m0, s17, 1792
	s_nop 0
	global_load_lds_dwordx4 v[48:49], off offset:256
	v_mfma_f32_16x16x32_bf16 v[14:17], v[56:59], v[52:55], 0
	v_mfma_f32_16x16x32_bf16 v[6:9], v[60:63], v[52:55], 0
	s_waitcnt vmcnt(9)
	ds_read_b128 v[64:67], v50 offset:3072
	ds_read_b128 v[68:71], v50 offset:4096
	ds_read_b128 v[72:75], v50 offset:5120
	s_waitcnt lgkmcnt(0)
	s_add_i32 m0, s17, 2752
	s_nop 0
	global_load_lds_dwordx4 v[44:45], off offset:320
	s_add_i32 m0, s17, 3776
	s_nop 0
	global_load_lds_dwordx4 v[46:47], off offset:320
	s_add_i32 m0, s17, 4800
	s_nop 0
	global_load_lds_dwordx4 v[48:49], off offset:320
	v_mfma_f32_16x16x32_bf16 v[14:17], v[68:71], v[64:67], v[14:17]
	v_mfma_f32_16x16x32_bf16 v[6:9], v[72:75], v[64:67], v[6:9]
	s_waitcnt vmcnt(9)
	ds_read_b128 v[52:55], v50 offset:6144
	ds_read_b128 v[56:59], v50 offset:7168
	ds_read_b128 v[60:63], v50 offset:8192
	s_waitcnt lgkmcnt(0)
	s_add_i32 m0, s17, 5760
	s_nop 0
	global_load_lds_dwordx4 v[44:45], off offset:384
	s_add_i32 m0, s17, 6784
	s_nop 0
	global_load_lds_dwordx4 v[46:47], off offset:384
	s_add_i32 m0, s17, 7808
	s_nop 0
	global_load_lds_dwordx4 v[48:49], off offset:384
	v_mfma_f32_16x16x32_bf16 v[14:17], v[56:59], v[52:55], v[14:17]
	v_mfma_f32_16x16x32_bf16 v[6:9], v[60:63], v[52:55], v[6:9]
	s_waitcnt vmcnt(9)
	ds_read_b128 v[64:67], v50 offset:9216
	ds_read_b128 v[68:71], v50 offset:10240
	ds_read_b128 v[72:75], v50 offset:11264
	s_waitcnt lgkmcnt(0)
	s_add_i32 m0, s17, 8768
	s_nop 0
	global_load_lds_dwordx4 v[44:45], off offset:448
	s_add_i32 m0, s17, 9792
	s_nop 0
	global_load_lds_dwordx4 v[46:47], off offset:448
	s_add_i32 m0, s17, 10816
	s_nop 0
	global_load_lds_dwordx4 v[48:49], off offset:448
	v_mfma_f32_16x16x32_bf16 v[14:17], v[68:71], v[64:67], v[14:17]
	v_mfma_f32_16x16x32_bf16 v[6:9], v[72:75], v[64:67], v[6:9]
	s_waitcnt vmcnt(9)
	ds_read_b128 v[52:55], v50 offset:0
	ds_read_b128 v[56:59], v50 offset:1024
	ds_read_b128 v[60:63], v50 offset:2048
	s_waitcnt lgkmcnt(0)
	s_sub_i32 m0, s17, 512
	s_nop 0
	global_load_lds_dwordx4 v[44:45], off offset:512
	s_add_i32 m0, s17, 512
	s_nop 0
	global_load_lds_dwordx4 v[46:47], off offset:512
	s_add_i32 m0, s17, 1536
	s_nop 0
	global_load_lds_dwordx4 v[48:49], off offset:512
	v_mfma_f32_16x16x32_bf16 v[14:17], v[56:59], v[52:55], v[14:17]
	v_mfma_f32_16x16x32_bf16 v[6:9], v[60:63], v[52:55], v[6:9]
	s_waitcnt vmcnt(9)
	ds_read_b128 v[64:67], v50 offset:3072
	ds_read_b128 v[68:71], v50 offset:4096
	ds_read_b128 v[72:75], v50 offset:5120
	s_waitcnt lgkmcnt(0)
	s_add_i32 m0, s17, 2496
	s_nop 0
	global_load_lds_dwordx4 v[44:45], off offset:576
	s_add_i32 m0, s17, 3520
	s_nop 0
	global_load_lds_dwordx4 v[46:47], off offset:576
	s_add_i32 m0, s17, 4544
	s_nop 0
	global_load_lds_dwordx4 v[48:49], off offset:576
	v_mfma_f32_16x16x32_bf16 v[14:17], v[68:71], v[64:67], v[14:17]
	v_mfma_f32_16x16x32_bf16 v[6:9], v[72:75], v[64:67], v[6:9]
	s_waitcnt vmcnt(9)
	ds_read_b128 v[52:55], v50 offset:6144
	ds_read_b128 v[56:59], v50 offset:7168
	ds_read_b128 v[60:63], v50 offset:8192
	s_waitcnt lgkmcnt(0)
	s_add_i32 m0, s17, 5504
	s_nop 0
	global_load_lds_dwordx4 v[44:45], off offset:640
	s_add_i32 m0, s17, 6528
	s_nop 0
	global_load_lds_dwordx4 v[46:47], off offset:640
	s_add_i32 m0, s17, 7552
	s_nop 0
	global_load_lds_dwordx4 v[48:49], off offset:640
	v_mfma_f32_16x16x32_bf16 v[14:17], v[56:59], v[52:55], v[14:17]
	v_mfma_f32_16x16x32_bf16 v[6:9], v[60:63], v[52:55], v[6:9]
	s_waitcnt vmcnt(9)
	ds_read_b128 v[64:67], v50 offset:9216
	ds_read_b128 v[68:71], v50 offset:10240
	ds_read_b128 v[72:75], v50 offset:11264
	s_waitcnt lgkmcnt(0)
	v_mfma_f32_16x16x32_bf16 v[14:17], v[68:71], v[64:67], v[14:17]
	v_mfma_f32_16x16x32_bf16 v[6:9], v[72:75], v[64:67], v[6:9]
	s_waitcnt vmcnt(6)
	ds_read_b128 v[52:55], v50 offset:0
	ds_read_b128 v[56:59], v50 offset:1024
	ds_read_b128 v[60:63], v50 offset:2048
	s_waitcnt lgkmcnt(0)
	v_mfma_f32_16x16x32_bf16 v[14:17], v[56:59], v[52:55], v[14:17]
	v_mfma_f32_16x16x32_bf16 v[6:9], v[60:63], v[52:55], v[6:9]
	s_waitcnt vmcnt(3)
	ds_read_b128 v[64:67], v50 offset:3072
	ds_read_b128 v[68:71], v50 offset:4096
	ds_read_b128 v[72:75], v50 offset:5120
	s_waitcnt lgkmcnt(0)
	v_mfma_f32_16x16x32_bf16 v[14:17], v[68:71], v[64:67], v[14:17]
	v_mfma_f32_16x16x32_bf16 v[6:9], v[72:75], v[64:67], v[6:9]
	s_waitcnt vmcnt(0)
	ds_read_b128 v[52:55], v50 offset:6144
	ds_read_b128 v[56:59], v50 offset:7168
	ds_read_b128 v[60:63], v50 offset:8192
	s_waitcnt lgkmcnt(0)
	v_mfma_f32_16x16x32_bf16 v[14:17], v[56:59], v[52:55], v[14:17]
	v_mfma_f32_16x16x32_bf16 v[6:9], v[60:63], v[52:55], v[6:9]
	s_nop 6
	ds_write_b128 v30, v[14:17]
	ds_write_b128 v30, v[6:9] offset:16
	s_waitcnt lgkmcnt(0)
	s_barrier
	s_cbranch_vccnz .LBB0_1087
	v_add_u32_e32 v24, 0, v13
	ds_read_b128 v[6:9], v24
	ds_read_b128 v[14:17], v24 offset:16
	s_ashr_i32 s11, s10, 31
	s_waitcnt lgkmcnt(1)
	v_pk_add_f32 v[10:11], v[8:9], 0 op_sel_hi:[1,0]
	v_pk_add_f32 v[18:19], v[6:7], 0 op_sel_hi:[1,0]
	ds_read_b128 v[6:9], v24 offset:2048
	s_waitcnt lgkmcnt(1)
	v_pk_add_f32 v[16:17], v[16:17], 0 op_sel_hi:[1,0]
	v_pk_add_f32 v[14:15], v[14:15], 0 op_sel_hi:[1,0]
	s_waitcnt lgkmcnt(0)
	v_pk_add_f32 v[10:11], v[10:11], v[8:9]
	v_pk_add_f32 v[18:19], v[18:19], v[6:7]
	ds_read_b128 v[6:9], v24 offset:2064
	s_waitcnt lgkmcnt(0)
	v_pk_add_f32 v[16:17], v[16:17], v[8:9]
	v_pk_add_f32 v[14:15], v[14:15], v[6:7]
	ds_read_b128 v[6:9], v24 offset:4096
	s_waitcnt lgkmcnt(0)
	v_pk_add_f32 v[10:11], v[10:11], v[8:9]
	v_pk_add_f32 v[18:19], v[18:19], v[6:7]
	ds_read_b128 v[6:9], v24 offset:4112
	s_waitcnt lgkmcnt(0)
	v_pk_add_f32 v[16:17], v[16:17], v[8:9]
	v_pk_add_f32 v[14:15], v[14:15], v[6:7]
	ds_read_b128 v[6:9], v24 offset:6144
	s_waitcnt lgkmcnt(0)
	v_pk_add_f32 v[10:11], v[10:11], v[8:9]
	v_pk_add_f32 v[18:19], v[18:19], v[6:7]
	ds_read_b128 v[6:9], v24 offset:6160
	s_waitcnt lgkmcnt(0)
	v_pk_add_f32 v[16:17], v[16:17], v[8:9]
	v_pk_add_f32 v[14:15], v[14:15], v[6:7]
	ds_read_b128 v[6:9], v24 offset:8192
	s_waitcnt lgkmcnt(0)
	v_pk_add_f32 v[10:11], v[10:11], v[8:9]
	v_pk_add_f32 v[18:19], v[18:19], v[6:7]
	ds_read_b128 v[6:9], v24 offset:8208
	s_waitcnt lgkmcnt(0)
	v_pk_add_f32 v[16:17], v[16:17], v[8:9]
	v_pk_add_f32 v[14:15], v[14:15], v[6:7]
	ds_read_b128 v[6:9], v24 offset:10240
	s_waitcnt lgkmcnt(0)
	v_pk_add_f32 v[10:11], v[10:11], v[8:9]
	v_pk_add_f32 v[18:19], v[18:19], v[6:7]
	ds_read_b128 v[6:9], v24 offset:10256
	s_waitcnt lgkmcnt(0)
	v_pk_add_f32 v[16:17], v[16:17], v[8:9]
	v_pk_add_f32 v[14:15], v[14:15], v[6:7]
	ds_read_b128 v[6:9], v24 offset:12288
	s_waitcnt lgkmcnt(0)
	v_pk_add_f32 v[10:11], v[10:11], v[8:9]
	v_pk_add_f32 v[18:19], v[18:19], v[6:7]
	ds_read_b128 v[6:9], v24 offset:12304
	s_waitcnt lgkmcnt(0)
	v_pk_add_f32 v[20:21], v[16:17], v[8:9]
	v_pk_add_f32 v[22:23], v[14:15], v[6:7]
	ds_read_b128 v[6:9], v24 offset:14336
	ds_read_b128 v[14:17], v24 offset:14352
	s_waitcnt lgkmcnt(1)
	v_pk_add_f32 v[8:9], v[10:11], v[8:9]
	s_waitcnt lgkmcnt(0)
	v_pk_add_f32 v[10:11], v[22:23], v[14:15]
	v_or_b32_e32 v14, 0x4000, v5
	v_lshlrev_b32_e32 v194, 11, v14
	v_pk_add_f32 v[18:19], v[18:19], v[6:7]
	v_pk_add_f32 v[6:7], v[20:21], v[16:17]
	v_lshl_add_u64 v[16:17], s[0:1], 0, v[194:195]
	v_lshl_add_u64 v[16:17], s[10:11], 1, v[16:17]
	v_mov_b32_e32 v5, v195
	v_lshl_add_u64 v[16:17], v[16:17], 0, v[4:5]
	global_load_dwordx2 v[20:21], v[16:17], off
	global_load_dwordx2 v[22:23], v[16:17], off offset:32
	s_waitcnt vmcnt(0) lgkmcnt(0)
	v_lshlrev_b32_e32 v24, 16, v20
	v_and_b32_e32 v25, 0xffff0000, v20
	v_lshlrev_b32_e32 v20, 16, v21
	v_and_b32_e32 v21, 0xffff0000, v21
	v_pk_add_f32 v[18:19], v[18:19], v[24:25]
	v_pk_add_f32 v[8:9], v[8:9], v[20:21]
	v_cvt_pk_bf16_f32 v18, v18, v19
	v_cvt_pk_bf16_f32 v19, v8, v9
	v_lshlrev_b32_e32 v8, 16, v22
	v_and_b32_e32 v9, 0xffff0000, v22
	v_pk_add_f32 v[8:9], v[10:11], v[8:9]
	v_lshlrev_b32_e32 v10, 16, v23
	v_and_b32_e32 v11, 0xffff0000, v23
	v_pk_add_f32 v[6:7], v[6:7], v[10:11]
	v_cvt_pk_bf16_f32 v8, v8, v9
	v_cvt_pk_bf16_f32 v9, v6, v7
	v_and_b32_e32 v6, 0xffff0000, v18
	v_lshlrev_b32_e32 v5, 16, v18
	v_and_b32_e32 v10, 0xffff0000, v19
	v_mul_f32_e32 v6, v6, v6
	v_lshlrev_b32_e32 v7, 16, v19
	v_fmac_f32_e32 v6, v5, v5
	v_mul_f32_e32 v5, v10, v10
	global_store_dwordx2 v[16:17], v[18:19], off
	global_store_dwordx2 v[16:17], v[8:9], off offset:32
	v_lshlrev_b32_e32 v11, 16, v8
	v_and_b32_e32 v8, 0xffff0000, v8
	v_fmac_f32_e32 v5, v7, v7
	v_add_f32_e32 v5, v6, v5
	v_mul_f32_e32 v6, v8, v8
	v_lshlrev_b32_e32 v15, 16, v9
	v_and_b32_e32 v9, 0xffff0000, v9
	v_fmac_f32_e32 v6, v11, v11
	v_add_f32_e32 v5, v5, v6
	v_mul_f32_e32 v6, v9, v9
	v_fmac_f32_e32 v6, v15, v15
	v_and_b32_e32 v7, 64, v243
	v_add_f32_e32 v5, v6, v5
	v_xor_b32_e32 v6, 16, v243
	v_add_u32_e32 v7, 64, v7
	v_cmp_lt_i32_e32 vcc, v6, v7
	s_nop 1
	v_cndmask_b32_e32 v6, v243, v6, vcc
	v_lshlrev_b32_e32 v6, 2, v6
	ds_bpermute_b32 v6, v6, v5
	s_waitcnt lgkmcnt(0)
	v_add_f32_e32 v5, v5, v6
	v_xor_b32_e32 v6, 32, v243
	v_cmp_lt_i32_e32 vcc, v6, v7
	s_nop 1
	v_cndmask_b32_e32 v6, v243, v6, vcc
	v_lshlrev_b32_e32 v6, 2, v6
	ds_bpermute_b32 v6, v6, v5
	s_and_saveexec_b64 s[2:3], s[4:5]
	s_cbranch_execz .LBB0_1086
	s_waitcnt lgkmcnt(0)
	v_add_f32_e32 v5, v5, v6
	s_mov_b32 s10, 0x4b800000
	v_fma_f32 v5, v5, s10, 0.5
	v_trunc_f32_e32 v5, v5
	v_mul_f32_e32 v6, 0x2f800000, v5
	v_floor_f32_e32 v7, v6
	v_fmac_f32_e32 v5, 0xcf800000, v7
	v_cvt_u32_f32_e32 v6, v5
	v_cvt_u32_f32_e32 v7, v7
	v_lshlrev_b32_e32 v194, 3, v14
	v_lshl_add_u64 v[8:9], s[6:7], 0, v[194:195]
	global_atomic_add_x2 v[8:9], v[6:7], off
	s_branch .LBB0_1086
